# attention key loop unrolled by two with two landing register sets: K/V tiles fetched two tiles ahead (on top of combined build)
# speedup vs baseline: 1.0055x; 1.0009x over previous
; #define LAS __attribute__((address_space(3)))
; __device__ __forceinline__ void attn_mfma_item(const bf16* u, bf16* y, const float* cl, const float* tot, LAS unsigned char* wl, int item, int lane) {
;     ...
;     f32x16 O0, O1;
; #pragma unroll
;     for (int i = 0; i < 16; ++i) { O0[i] = 0.f; O1[i] = 0.f; }
;     float mrun = -1e30f, lsum = 0.f, Rsb = 1.f, Doff = 0.f;
;     const float clt = fox ? clh[t] : 0.f;
;     LAS float* gl = (LAS float*)(wl + 4608);
;     const int trbase = (4 * hi + ((lane >> 2) & 3)) * PV64 + (16 * ((lane >> 4) & 1) + 4 * (lane & 3)) * 2;
;     const unsigned lane_off = (unsigned)((lane >> 3) * NU + 8 * (lane & 7)) * 2u;
;     v4u kn[4], vn[4]; float gn = 0.f;
;     { const char* tb = ubc + (size_t)(qb * 32) * NU * 2;
; #pragma unroll
;       for (int i = 0; i < 4; ++i) { kn[i] = *(const v4u*)(tb + (size_t)(8 * i * NU + koff) * 2 + lane_off); vn[i] = *(const v4u*)(tb + (size_t)(8 * i * NU + voff) * 2 + lane_off); }
;       if (fox) gn = clh[qb * 32 + r]; }
;     LAS unsigned char* kl = wl + 4736;
;     const int kfoff = r * PV64 + 16 * hi;
;     const float SC2 = 0.125f * 1.4426950408889634f;
;     { LAS unsigned char* z = wl + 9344 + (lane >> 3) * PV64 + 16 * (lane & 7);
; #pragma unroll
;       for (int i = 0; i < 4; ++i) *(LAS v4u*)(z + 8 * i * PV64) = (v4u){0u, 0u, 0u, 0u}; }
;     s16x8 Pp0 = {0, 0, 0, 0, 0, 0, 0, 0}, Pp1 = {0, 0, 0, 0, 0, 0, 0, 0};
;     int vlast = 0;
;     ...
;         const bool diag = (jt == qb);
;         const int vcur = ((qb - jt) & 1) ? 9344 : 0, vprev = 9344 - vcur; vlast = vcur;
;         { LAS unsigned char* dk = kl + (lane >> 3) * PV64 + 16 * (lane & 7); LAS unsigned char* dv = wl + vcur + (lane >> 3) * PV64 + 16 * (lane & 7);
; #pragma unroll
;           for (int i = 0; i < 4; ++i) { *(LAS v4u*)(dk + 8 * i * PV64) = kn[i]; *(LAS v4u*)(dv + 8 * i * PV64) = vn[i]; } }
;         if (fox) gl[r] = -gn;
;         if (jt > 0) { const char* tb = ubc + (size_t)((jt - 1) * 32) * NU * 2;
; #pragma unroll
;           for (int i = 0; i < 4; ++i) { kn[i] = *(const v4u*)(tb + (size_t)(8 * i * NU + koff) * 2 + lane_off); vn[i] = *(const v4u*)(tb + (size_t)(8 * i * NU + voff) * 2 + lane_off); }
;           if (fox) gn = clh[(jt - 1) * 32 + r]; }
.LBB0_747:
	s_mov_b32 s84, s85
	s_mov_b32 s86, s85
	s_mov_b32 s87, s85
	v_mov_b64_e32 v[4:5], s[84:85]
	v_mov_b64_e32 v[6:7], s[86:87]
	s_cmpk_gt_i32 s33, 0x13ff
	ds_write_b128 v207, v[4:7] offset:9344
	ds_write_b128 v207, v[4:7] offset:10496
	ds_write_b128 v207, v[4:7] offset:11648
	ds_write_b128 v207, v[4:7] offset:12800
	s_cbranch_scc1 .LBB0_775
	s_waitcnt vmcnt(8)
	v_mov_b32_e32 v16, v3
	v_mov_b32_e32 v17, v3
	v_mov_b32_e32 v2, v3
	v_mov_b32_e32 v4, v3
	v_mov_b32_e32 v5, v3
	v_mov_b32_e32 v6, v3
	v_mov_b32_e32 v7, v3
	v_mov_b32_e32 v8, v3
	v_mov_b32_e32 v9, v3
	v_mov_b32_e32 v10, v3
	v_mov_b32_e32 v11, v3
	v_mov_b32_e32 v12, v3
	v_mov_b32_e32 v13, v3
	v_mov_b32_e32 v14, v3
	v_mov_b32_e32 v15, v3
	v_mov_b64_e32 v[34:35], v[16:17]
	v_mov_b32_e32 v52, 0
	v_mov_b64_e32 v[32:33], v[14:15]
	v_mov_b64_e32 v[30:31], v[12:13]
	v_mov_b64_e32 v[28:29], v[10:11]
	v_mov_b64_e32 v[26:27], v[8:9]
	v_mov_b64_e32 v[24:25], v[6:7]
	v_mov_b64_e32 v[22:23], v[4:5]
	v_mov_b64_e32 v[20:21], v[2:3]
	v_mov_b64_e32 v[18:19], v[16:17]
	s_lshl_b32 s84, s94, 3
	v_lshl_add_u64 v[122:123], s[70:71], 0, v[150:151]
	s_add_u32 s54, s54, s70
	s_addc_u32 s55, s55, s71
	s_add_u32 s56, s56, s70
	s_addc_u32 s57, s57, s71
	s_add_u32 s58, s58, s70
	s_addc_u32 s59, s59, s71
	s_add_u32 s60, s60, s70
	s_addc_u32 s61, s61, s71
	s_add_u32 s62, s62, s70
	s_addc_u32 s63, s63, s71
	s_add_u32 s64, s64, s70
	s_addc_u32 s65, s65, s71
	s_add_u32 s66, s66, s70
	s_addc_u32 s67, s67, s71
	s_add_u32 s68, s68, s70
	s_addc_u32 s69, s69, s71
	s_sub_i32 s83, s73, 32
	s_mov_b32 s73, 0
	v_mov_b32_e32 v136, 1.0
	v_mov_b32_e32 v121, 0
	v_mov_b32_e32 v138, 0xf149f2ca
	v_mov_b64_e32 v[16:17], v[14:15]
	v_mov_b64_e32 v[14:15], v[12:13]
	v_mov_b64_e32 v[12:13], v[10:11]
	v_mov_b64_e32 v[10:11], v[8:9]
	v_mov_b64_e32 v[8:9], v[6:7]
	v_mov_b64_e32 v[6:7], v[4:5]
	v_mov_b64_e32 v[4:5], v[2:3]
	v_mov_b32_e32 v137, 0
	v_mov_b32_e32 v53, v52
	v_mov_b32_e32 v54, v52
	v_mov_b32_e32 v55, v52
	v_mov_b32_e32 v116, v52
	v_mov_b32_e32 v117, v52
	v_mov_b32_e32 v118, v52
	v_mov_b32_e32 v119, v52
	s_cmp_lt_u32 s1, 1
	s_cbranch_scc1 .Lf_no_t1
	v_mad_u32_u24 v226, s83, v215, v150
	s_nop 0
	global_load_dwordx4 v[228:231], v226, s[54:55]
	global_load_dwordx4 v[232:235], v226, s[56:57]
	global_load_dwordx4 v[236:239], v226, s[58:59]
	global_load_dwordx4 v[240:243], v226, s[60:61]
	global_load_dwordx4 v[244:247], v226, s[62:63]
	global_load_dwordx4 v[172:175], v226, s[64:65]
	global_load_dwordx4 v[176:179], v226, s[66:67]
	global_load_dwordx4 v[194:197], v226, s[68:69]
	s_and_b64 vcc, exec, s[92:93]
	s_cbranch_vccnz .Lf_no_t1
	v_add_lshl_u32 v227, s83, v145, 2
	s_nop 0
	global_load_dword v248, v227, s[52:53]
.Lf_no_t1:
	s_branch .LBB0_750
.LBB0_749:
	s_andn2_b64 vcc, exec, s[70:71]
	s_cbranch_vccz .LBB0_776
.LBB0_750:
	s_bfe_i32 s33, s73, 0x10000
	s_and_b32 s33, s33, 0x2480
	v_add_u32_e32 v1, s33, v207
	s_and_b64 vcc, exec, s[92:93]
	s_cmp_eq_u32 s1, 0
	s_cbranch_scc1 .Lfx_l7
	s_waitcnt vmcnt(15)
	ds_write_b128 v207, v[84:87] offset:4736
	s_waitcnt vmcnt(14)
	ds_write_b128 v1, v[88:91]
	s_waitcnt vmcnt(13)
	ds_write_b128 v207, v[92:95] offset:5888
	s_waitcnt vmcnt(12)
	ds_write_b128 v1, v[96:99] offset:1152
	s_waitcnt vmcnt(11)
	ds_write_b128 v207, v[100:103] offset:7040
	s_waitcnt vmcnt(10)
	ds_write_b128 v1, v[104:107] offset:2304
	s_waitcnt vmcnt(9)
	ds_write_b128 v207, v[108:111] offset:8192
	s_waitcnt vmcnt(8)
	ds_write_b128 v1, v[112:115] offset:3456
	s_branch .Lfx_le
.Lfx_l7:
	s_waitcnt vmcnt(7)
	ds_write_b128 v207, v[84:87] offset:4736
	s_waitcnt vmcnt(6)
	ds_write_b128 v1, v[88:91]
	s_waitcnt vmcnt(5)
	ds_write_b128 v207, v[92:95] offset:5888
	s_waitcnt vmcnt(4)
	ds_write_b128 v1, v[96:99] offset:1152
	s_waitcnt vmcnt(3)
	ds_write_b128 v207, v[100:103] offset:7040
	s_waitcnt vmcnt(2)
	ds_write_b128 v1, v[104:107] offset:2304
	s_waitcnt vmcnt(1)
	ds_write_b128 v207, v[108:111] offset:8192
	s_waitcnt vmcnt(0)
	ds_write_b128 v1, v[112:115] offset:3456
.Lfx_le:
	s_cbranch_vccnz .LBB0_752
	v_xor_b32_e32 v1, 0x80000000, v135
	ds_write_b32 v186, v1 offset:4608
.LBB0_752:
	s_cmp_lg_u32 s1, 0
	s_cselect_b64 s[86:87], -1, 0
	s_cmp_lt_u32 s1, 2
	s_cbranch_scc1 .LBB0_755
	s_sub_i32 s70, s83, 32
	v_mad_u32_u24 v226, s70, v215, v150
	s_nop 0
	global_load_dwordx4 v[84:87], v226, s[54:55]
	global_load_dwordx4 v[88:91], v226, s[56:57]
	global_load_dwordx4 v[92:95], v226, s[58:59]
	global_load_dwordx4 v[96:99], v226, s[60:61]
	global_load_dwordx4 v[100:103], v226, s[62:63]
	global_load_dwordx4 v[104:107], v226, s[64:65]
	global_load_dwordx4 v[108:111], v226, s[66:67]
	global_load_dwordx4 v[112:115], v226, s[68:69]
	s_and_b64 vcc, exec, s[92:93]
	s_cbranch_vccnz .LBB0_755
	v_add_lshl_u32 v227, s70, v145, 2
	s_nop 0
	global_load_dword v135, v227, s[52:53]

; #define LAS __attribute__((address_space(3)))
; __device__ __forceinline__ void attn_mfma_item(const bf16* u, bf16* y, const float* cl, const float* tot, LAS unsigned char* wl, int item, int lane) {
;     ...
;         const bool diag = (jt == qb);
;         const int vcur = ((qb - jt) & 1) ? 9344 : 0, vprev = 9344 - vcur; vlast = vcur;
;         { LAS unsigned char* dk = kl + (lane >> 3) * PV64 + 16 * (lane & 7); LAS unsigned char* dv = wl + vcur + (lane >> 3) * PV64 + 16 * (lane & 7);
; #pragma unroll
;           for (int i = 0; i < 4; ++i) { *(LAS v4u*)(dk + 8 * i * PV64) = kn[i]; *(LAS v4u*)(dv + 8 * i * PV64) = vn[i]; } }
;         if (fox) gl[r] = -gn;
;         if (jt > 0) { const char* tb = ubc + (size_t)((jt - 1) * 32) * NU * 2;
; #pragma unroll
;           for (int i = 0; i < 4; ++i) { kn[i] = *(const v4u*)(tb + (size_t)(8 * i * NU + koff) * 2 + lane_off); vn[i] = *(const v4u*)(tb + (size_t)(8 * i * NU + voff) * 2 + lane_off); }
;           if (fox) gn = clh[(jt - 1) * 32 + r]; }
.LBB0_773:
	s_andn2_b64 vcc, exec, s[70:71]
	s_mov_b64 s[70:71], -1
	s_cbranch_vccnz .Lfy_749
	s_add_i32 s1, s1, -1
	s_sub_i32 s83, s83, 32
	s_add_i32 s73, s73, 1
	s_mov_b64 s[70:71], 0
	s_branch .Lfy_749
.Lfy_749:
	s_andn2_b64 vcc, exec, s[70:71]
	s_cbranch_vccz .LBB0_776
.Lfy_750:
	s_bfe_i32 s33, s73, 0x10000
	s_and_b32 s33, s33, 0x2480
	v_add_u32_e32 v1, s33, v207
	s_and_b64 vcc, exec, s[92:93]
	s_cmp_eq_u32 s1, 0
	s_cbranch_scc1 .Lfy2_l7
	s_waitcnt vmcnt(15)
	ds_write_b128 v207, v[228:231] offset:4736
	s_waitcnt vmcnt(14)
	ds_write_b128 v1, v[232:235]
	s_waitcnt vmcnt(13)
	ds_write_b128 v207, v[236:239] offset:5888
	s_waitcnt vmcnt(12)
	ds_write_b128 v1, v[240:243] offset:1152
	s_waitcnt vmcnt(11)
	ds_write_b128 v207, v[244:247] offset:7040
	s_waitcnt vmcnt(10)
	ds_write_b128 v1, v[172:175] offset:2304
	s_waitcnt vmcnt(9)
	ds_write_b128 v207, v[176:179] offset:8192
	s_waitcnt vmcnt(8)
	ds_write_b128 v1, v[194:197] offset:3456
	s_branch .Lfy2_le
.Lfy2_l7:
	s_waitcnt vmcnt(7)
	ds_write_b128 v207, v[228:231] offset:4736
	s_waitcnt vmcnt(6)
	ds_write_b128 v1, v[232:235]
	s_waitcnt vmcnt(5)
	ds_write_b128 v207, v[236:239] offset:5888
	s_waitcnt vmcnt(4)
	ds_write_b128 v1, v[240:243] offset:1152
	s_waitcnt vmcnt(3)
	ds_write_b128 v207, v[244:247] offset:7040
	s_waitcnt vmcnt(2)
	ds_write_b128 v1, v[172:175] offset:2304
	s_waitcnt vmcnt(1)
	ds_write_b128 v207, v[176:179] offset:8192
	s_waitcnt vmcnt(0)
	ds_write_b128 v1, v[194:197] offset:3456
.Lfy2_le:
	s_cbranch_vccnz .Lfy_752
	v_xor_b32_e32 v1, 0x80000000, v248
	ds_write_b32 v186, v1 offset:4608
.Lfy_752:
	s_cmp_lg_u32 s1, 0
	s_cselect_b64 s[86:87], -1, 0
	s_cmp_lt_u32 s1, 2
	s_cbranch_scc1 .Lfy_755
	s_sub_i32 s70, s83, 32
	v_mad_u32_u24 v226, s70, v215, v150
	s_nop 0
	global_load_dwordx4 v[228:231], v226, s[54:55]
	global_load_dwordx4 v[232:235], v226, s[56:57]
	global_load_dwordx4 v[236:239], v226, s[58:59]
	global_load_dwordx4 v[240:243], v226, s[60:61]
	global_load_dwordx4 v[244:247], v226, s[62:63]
	global_load_dwordx4 v[172:175], v226, s[64:65]
	global_load_dwordx4 v[176:179], v226, s[66:67]
	global_load_dwordx4 v[194:197], v226, s[68:69]
	s_and_b64 vcc, exec, s[92:93]
	s_cbranch_vccnz .Lfy_755
	v_add_lshl_u32 v227, s70, v145, 2
	s_nop 0
	global_load_dword v248, v227, s[52:53]

; #define LAS __attribute__((address_space(3)))
; __device__ __forceinline__ s16x4 tr_read(LAS const unsigned char* p) { return __builtin_bit_cast(s16x4, __builtin_amdgcn_ds_read_tr16_b64_v4i16((LAS s16x4*)p)); }
; __device__ __forceinline__ s16x8 cat8(s16x4 a, s16x4 b) { return (s16x8){a[0], a[1], a[2], a[3], b[0], b[1], b[2], b[3]}; }
; #define MFMA32(a, b, c) __builtin_amdgcn_mfma_f32_32x32x16_bf16(a, b, c, 0, 0, 0)
; __device__ __forceinline__ void attn_mfma_item(const bf16* u, bf16* y, const float* cl, const float* tot, LAS unsigned char* wl, int item, int lane) {
;     ...
;         if (!fox && __all(Rsb == 0.0f)) break;
;     }
;     { LAS const unsigned char* vb = wl + vlast + trbase;
;       const s16x8 V00 = cat8(tr_read(vb), tr_read(vb + 8 * PV64)), V01 = cat8(tr_read(vb + 16 * PV64), tr_read(vb + 24 * PV64));
;       const s16x8 V10 = cat8(tr_read(vb + 64), tr_read(vb + 8 * PV64 + 64)), V11 = cat8(tr_read(vb + 16 * PV64 + 64), tr_read(vb + 24 * PV64 + 64));
;       O0 = MFMA32(V00, Pp0, O0); O1 = MFMA32(V10, Pp0, O1); O0 = MFMA32(V01, Pp1, O0); O1 = MFMA32(V11, Pp1, O1); }
.LBB0_776:
	s_waitcnt vmcnt(0)
	v_mov_b32_e32 v1, s33
	s_movk_i32 s83, 0x2000
